# row sum with two independent accumulators (no dependent add chain in MFMA gaps)
# speedup vs baseline: 1.0079x; 1.0079x over previous
; DI void diff_core(unsigned char* smem, const u16* qptr, const u16* kbase, const u16* vtbase, int vld,
;                   int ntb, int ntw, int nvalid, int ks0, const float* lut, int qpos, bool active, bool grpB,
;                   f32x16 (&O)[4], float& l_out) {
;     ...
;   auto pv = [&](int slot) {
;     if (grpB) __builtin_amdgcn_s_setprio(2); else __builtin_amdgcn_s_setprio(1);
;     const LAS unsigned char* b = lds + slot * D_SLOT;
;     bf16x8 va[4], vb[4];
; #pragma unroll
;     for (int tt = 0; tt < 4; ++tt) va[tt] = *reinterpret_cast<const LAS bf16x8*>(b + voff[0] + tt * 32 * 128);
; #pragma unroll
;     for (int tt = 0; tt < 4; ++tt) vb[tt] = *reinterpret_cast<const LAS bf16x8*>(b + voff[1] + tt * 32 * 128);
;     {
;       const bf16x8 pf = __builtin_bit_cast(bf16x8, P[0]);
; #pragma unroll
;       for (int tt = 0; tt < 4; ++tt) O[tt] = MFMA(va[tt], pf, O[tt]);
;     }
; #pragma unroll
;     for (int tt = 0; tt < 4; ++tt) va[tt] = *reinterpret_cast<const LAS bf16x8*>(b + voff[2] + tt * 32 * 128);
;     {
;       const bf16x8 pf = __builtin_bit_cast(bf16x8, P[1]);
; #pragma unroll
;       for (int tt = 0; tt < 4; ++tt) O[tt] = MFMA(vb[tt], pf, O[tt]);
;     }
; #pragma unroll
;     for (int tt = 0; tt < 4; ++tt) vb[tt] = *reinterpret_cast<const LAS bf16x8*>(b + voff[3] + tt * 32 * 128);
;     {
;       const bf16x8 pf = __builtin_bit_cast(bf16x8, P[2]);
; #pragma unroll
;       for (int tt = 0; tt < 4; ++tt) O[tt] = MFMA(va[tt], pf, O[tt]);
;     }
;     {
;       const bf16x8 pf = __builtin_bit_cast(bf16x8, P[3]);
; #pragma unroll
;       for (int tt = 0; tt < 4; ++tt) O[tt] = MFMA(vb[tt], pf, O[tt]);
;     }
;     __builtin_amdgcn_sched_group_barrier(0x100, 8, 0);
;     ...
;     float ps = 0.f;
; #pragma unroll
;     for (int kb = 0; kb < 2; ++kb)
; #pragma unroll
;       for (int i = 0; i < 16; ++i) {
;         const float pe = __builtin_amdgcn_exp2f(S[kb][i]);
;         S[kb][i] = pe;
;         ps += pe;
;       }
;     l += ps;
; #pragma unroll
;     for (int kb = 0; kb < 2; ++kb)
; #pragma unroll
;       for (int s2 = 0; s2 < 2; ++s2) {
;         u32x4 pk;
;         pk.x = pack2(S[kb][8 * s2 + 0], S[kb][8 * s2 + 1]);
;         pk.y = pack2(S[kb][8 * s2 + 2], S[kb][8 * s2 + 3]);
;         pk.z = pack2(S[kb][8 * s2 + 4], S[kb][8 * s2 + 5]);
;         pk.w = pack2(S[kb][8 * s2 + 6], S[kb][8 * s2 + 7]);
;         P[kb * 2 + s2] = pk;
;       }
.LBB0_360:
	s_add_i32 s66, s64, 0x101
	s_cmp_gt_u32 s66, s16
	s_cbranch_scc1 .LBB0_362
	s_setprio 2
	s_and_b32 s0, s65, 0x18000
	v_add_u32_e32 v248, s0, v197
	ds_read_b128 v[64:67], v248 offset:16384
	ds_read_b128 v[68:71], v248 offset:20480
	ds_read_b128 v[72:75], v248 offset:24576
	ds_read_b128 v[76:79], v248 offset:28672
	s_add_i32 s67, s65, 0xfffe8000
	s_and_b32 s67, s67, 0x18000
	v_cvt_pk_bf16_f32 v144, v96, v97
	v_cvt_pk_bf16_f32 v145, v98, v99
	v_cvt_pk_bf16_f32 v146, v100, v101
	v_cvt_pk_bf16_f32 v147, v102, v103
	v_add_f32_e32 v250, v97, v96
	v_add_f32_e32 v251, v99, v98
	s_waitcnt lgkmcnt(4)
	v_mfma_f32_32x32x16_bf16 v[48:63], v[200:203], v[144:147], v[48:63]
	v_cvt_pk_bf16_f32 v148, v104, v105
	v_add_f32_e32 v250, v100, v250
	v_add_f32_e32 v251, v101, v251
	v_add_u32_e32 v249, s0, v198
	ds_read_b128 v[80:83], v249 offset:16384
	ds_read_b128 v[84:87], v249 offset:20480
	ds_read_b128 v[88:91], v249 offset:24576
	ds_read_b128 v[92:95], v249 offset:28672
	v_mfma_f32_32x32x16_bf16 v[32:47], v[204:207], v[144:147], v[32:47]
	v_cvt_pk_bf16_f32 v149, v106, v107
	v_add_f32_e32 v250, v102, v250
	v_add_f32_e32 v251, v103, v251
	v_mfma_f32_32x32x16_bf16 v[16:31], v[208:211], v[144:147], v[16:31]
	v_cvt_pk_bf16_f32 v150, v108, v109
	v_add_f32_e32 v250, v104, v250
	v_add_f32_e32 v251, v105, v251
	v_mfma_f32_32x32x16_bf16 v[0:15], v[212:215], v[144:147], v[0:15]
	v_cvt_pk_bf16_f32 v151, v110, v111
	v_add_f32_e32 v250, v106, v250
	v_add_f32_e32 v251, v107, v251
	v_mfma_f32_32x32x16_bf16 v[48:63], v[216:219], v[148:151], v[48:63]
	v_cvt_pk_bf16_f32 v152, v112, v113
	v_add_f32_e32 v250, v108, v250
	v_add_f32_e32 v251, v109, v251
	v_mfma_f32_32x32x16_bf16 v[32:47], v[220:223], v[148:151], v[32:47]
	v_cvt_pk_bf16_f32 v153, v114, v115
	v_add_f32_e32 v250, v110, v250
	v_add_f32_e32 v251, v111, v251
	v_mfma_f32_32x32x16_bf16 v[16:31], v[224:227], v[148:151], v[16:31]
	v_cvt_pk_bf16_f32 v154, v116, v117
	v_add_f32_e32 v250, v112, v250
	v_add_f32_e32 v251, v113, v251
	v_mfma_f32_32x32x16_bf16 v[0:15], v[228:231], v[148:151], v[0:15]
	v_cvt_pk_bf16_f32 v155, v118, v119
	v_add_f32_e32 v250, v114, v250
	v_add_f32_e32 v251, v115, v251
	v_add_u32_e32 v248, s67, v177
	ds_read_b128 v[200:203], v248
	ds_read_b128 v[204:207], v248 offset:8192
	v_add_u32_e32 v249, s67, v178
	ds_read_b128 v[208:211], v249
	ds_read_b128 v[212:215], v249 offset:8192
	s_waitcnt lgkmcnt(8)
	v_mfma_f32_32x32x16_bf16 v[48:63], v[64:67], v[152:155], v[48:63]
	v_cvt_pk_bf16_f32 v156, v120, v121
	v_add_f32_e32 v250, v116, v250
	v_add_f32_e32 v251, v117, v251
	v_mfma_f32_32x32x16_bf16 v[32:47], v[68:71], v[152:155], v[32:47]
	v_cvt_pk_bf16_f32 v157, v122, v123
	v_add_f32_e32 v250, v118, v250
	v_add_f32_e32 v251, v119, v251
	v_mfma_f32_32x32x16_bf16 v[16:31], v[72:75], v[152:155], v[16:31]
	v_cvt_pk_bf16_f32 v158, v124, v125
	v_add_f32_e32 v250, v120, v250
	v_add_f32_e32 v251, v121, v251
	v_mfma_f32_32x32x16_bf16 v[0:15], v[76:79], v[152:155], v[0:15]
	v_cvt_pk_bf16_f32 v159, v126, v127
	v_add_f32_e32 v250, v122, v250
	v_add_f32_e32 v251, v123, v251
	v_add_u32_e32 v248, s67, v179
	ds_read_b128 v[216:219], v248
	ds_read_b128 v[220:223], v248 offset:8192
	v_add_u32_e32 v249, s67, v180
	ds_read_b128 v[224:227], v249
	ds_read_b128 v[228:231], v249 offset:8192
	s_waitcnt lgkmcnt(8)
	v_mfma_f32_32x32x16_bf16 v[48:63], v[80:83], v[156:159], v[48:63]
	v_add_f32_e32 v250, v124, v250
	v_add_f32_e32 v251, v125, v251
	v_mfma_f32_32x32x16_bf16 v[32:47], v[84:87], v[156:159], v[32:47]
	v_add_f32_e32 v250, v126, v250
	v_add_f32_e32 v251, v127, v251
	v_mfma_f32_32x32x16_bf16 v[16:31], v[88:91], v[156:159], v[16:31]
	v_add_f32_e32 v250, v250, v251
	v_mfma_f32_32x32x16_bf16 v[0:15], v[92:95], v[156:159], v[0:15]
	v_add_f32_e32 v181, v181, v250
	s_setprio 0

; DI void diff_core(unsigned char* smem, const u16* qptr, const u16* kbase, const u16* vtbase, int vld,
;                   int ntb, int ntw, int nvalid, int ks0, const float* lut, int qpos, bool active, bool grpB,
;                   f32x16 (&O)[4], float& l_out) {
;     ...
;   auto pv = [&](int slot) {
;     if (grpB) __builtin_amdgcn_s_setprio(2); else __builtin_amdgcn_s_setprio(1);
;     const LAS unsigned char* b = lds + slot * D_SLOT;
;     bf16x8 va[4], vb[4];
; #pragma unroll
;     for (int tt = 0; tt < 4; ++tt) va[tt] = *reinterpret_cast<const LAS bf16x8*>(b + voff[0] + tt * 32 * 128);
; #pragma unroll
;     for (int tt = 0; tt < 4; ++tt) vb[tt] = *reinterpret_cast<const LAS bf16x8*>(b + voff[1] + tt * 32 * 128);
;     {
;       const bf16x8 pf = __builtin_bit_cast(bf16x8, P[0]);
; #pragma unroll
;       for (int tt = 0; tt < 4; ++tt) O[tt] = MFMA(va[tt], pf, O[tt]);
;     }
; #pragma unroll
;     for (int tt = 0; tt < 4; ++tt) va[tt] = *reinterpret_cast<const LAS bf16x8*>(b + voff[2] + tt * 32 * 128);
;     {
;       const bf16x8 pf = __builtin_bit_cast(bf16x8, P[1]);
; #pragma unroll
;       for (int tt = 0; tt < 4; ++tt) O[tt] = MFMA(vb[tt], pf, O[tt]);
;     }
; #pragma unroll
;     for (int tt = 0; tt < 4; ++tt) vb[tt] = *reinterpret_cast<const LAS bf16x8*>(b + voff[3] + tt * 32 * 128);
;     {
;       const bf16x8 pf = __builtin_bit_cast(bf16x8, P[2]);
; #pragma unroll
;       for (int tt = 0; tt < 4; ++tt) O[tt] = MFMA(va[tt], pf, O[tt]);
;     }
;     {
;       const bf16x8 pf = __builtin_bit_cast(bf16x8, P[3]);
; #pragma unroll
;       for (int tt = 0; tt < 4; ++tt) O[tt] = MFMA(vb[tt], pf, O[tt]);
;     }
;     __builtin_amdgcn_sched_group_barrier(0x100, 8, 0);
;     ...
;     float ps = 0.f;
; #pragma unroll
;     for (int kb = 0; kb < 2; ++kb)
; #pragma unroll
;       for (int i = 0; i < 16; ++i) {
;         const float pe = __builtin_amdgcn_exp2f(S[kb][i]);
;         S[kb][i] = pe;
;         ps += pe;
;       }
;     l += ps;
; #pragma unroll
;     for (int kb = 0; kb < 2; ++kb)
; #pragma unroll
;       for (int s2 = 0; s2 < 2; ++s2) {
;         u32x4 pk;
;         pk.x = pack2(S[kb][8 * s2 + 0], S[kb][8 * s2 + 1]);
;         pk.y = pack2(S[kb][8 * s2 + 2], S[kb][8 * s2 + 3]);
;         pk.z = pack2(S[kb][8 * s2 + 4], S[kb][8 * s2 + 5]);
;         pk.w = pack2(S[kb][8 * s2 + 6], S[kb][8 * s2 + 7]);
;         P[kb * 2 + s2] = pk;
;       }
.LBB0_383:
	v_exp_f32_e32 v80, v80
	v_exp_f32_e32 v81, v81
	v_exp_f32_e32 v82, v82
	v_exp_f32_e32 v83, v83
	v_exp_f32_e32 v84, v84
	v_exp_f32_e32 v85, v85
	v_exp_f32_e32 v86, v86
	v_exp_f32_e32 v87, v87
	v_exp_f32_e32 v88, v88
	v_exp_f32_e32 v89, v89
	v_exp_f32_e32 v90, v90
	v_exp_f32_e32 v91, v91
	v_exp_f32_e32 v92, v92
	v_exp_f32_e32 v93, v93
	v_exp_f32_e32 v94, v94
	v_exp_f32_e32 v95, v95
	v_exp_f32_e32 v64, v64
	v_exp_f32_e32 v65, v65
	v_exp_f32_e32 v66, v66
	v_exp_f32_e32 v67, v67
	v_exp_f32_e32 v68, v68
	v_exp_f32_e32 v69, v69
	v_exp_f32_e32 v70, v70
	v_exp_f32_e32 v71, v71
	v_exp_f32_e32 v72, v72
	v_exp_f32_e32 v73, v73
	v_exp_f32_e32 v74, v74
	v_exp_f32_e32 v75, v75
	v_exp_f32_e32 v76, v76
	v_exp_f32_e32 v77, v77
	v_exp_f32_e32 v78, v78
	v_exp_f32_e32 v79, v79
	v_cvt_pk_bf16_f32 v144, v80, v81
	v_cvt_pk_bf16_f32 v145, v82, v83
	v_cvt_pk_bf16_f32 v146, v84, v85
	v_cvt_pk_bf16_f32 v147, v86, v87
	v_add_f32_e32 v250, v81, v80
	v_add_f32_e32 v251, v83, v82
.LBB0_384:
	s_waitcnt vmcnt(4)
	s_barrier
	s_andn2_b64 vcc, exec, s[0:1]
	s_cbranch_vccnz .LBB0_386
	s_setprio 2
	s_waitcnt lgkmcnt(0)
	v_mfma_f32_32x32x16_bf16 v[48:63], v[200:203], v[144:147], v[48:63]
	v_cvt_pk_bf16_f32 v148, v88, v89
	v_add_f32_e32 v250, v84, v250
	v_add_f32_e32 v251, v85, v251
	v_add_u32_e32 v97, s100, v186
	ds_read_b128 v[98:101], v97 offset:16384
	ds_read_b128 v[102:105], v97 offset:20480
	ds_read_b128 v[106:109], v97 offset:24576
	ds_read_b128 v[110:113], v97 offset:28672
	v_mfma_f32_32x32x16_bf16 v[32:47], v[204:207], v[144:147], v[32:47]
	v_cvt_pk_bf16_f32 v149, v90, v91
	v_add_f32_e32 v250, v86, v250
	v_add_f32_e32 v251, v87, v251
	v_add_u32_e32 v126, s100, v184
	ds_read_b128 v[114:117], v126 offset:16384
	ds_read_b128 v[118:121], v126 offset:20480
	ds_read_b128 v[122:125], v126 offset:24576
	ds_read_b128 v[196:199], v126 offset:28672
	v_mfma_f32_32x32x16_bf16 v[16:31], v[208:211], v[144:147], v[16:31]
	v_cvt_pk_bf16_f32 v150, v92, v93
	v_add_f32_e32 v250, v88, v250
	v_add_f32_e32 v251, v89, v251
	v_mfma_f32_32x32x16_bf16 v[0:15], v[212:215], v[144:147], v[0:15]
	v_cvt_pk_bf16_f32 v151, v94, v95
	v_add_f32_e32 v250, v90, v250
	v_add_f32_e32 v251, v91, v251
	v_mfma_f32_32x32x16_bf16 v[48:63], v[216:219], v[148:151], v[48:63]
	v_cvt_pk_bf16_f32 v152, v64, v65
	v_add_f32_e32 v250, v92, v250
	v_add_f32_e32 v251, v93, v251
	v_mfma_f32_32x32x16_bf16 v[32:47], v[220:223], v[148:151], v[32:47]
	v_cvt_pk_bf16_f32 v153, v66, v67
	v_add_f32_e32 v250, v94, v250
	v_add_f32_e32 v251, v95, v251
	v_mfma_f32_32x32x16_bf16 v[16:31], v[224:227], v[148:151], v[16:31]
	v_cvt_pk_bf16_f32 v154, v68, v69
	v_add_f32_e32 v250, v64, v250
	v_add_f32_e32 v251, v65, v251
	v_mfma_f32_32x32x16_bf16 v[0:15], v[228:231], v[148:151], v[0:15]
	v_cvt_pk_bf16_f32 v155, v70, v71
	v_add_f32_e32 v250, v66, v250
	v_add_f32_e32 v251, v67, v251
	v_add_u32_e32 v97, s101, v177
	ds_read_b128 v[200:203], v97
	ds_read_b128 v[204:207], v97 offset:8192
	v_add_u32_e32 v126, s101, v178
	ds_read_b128 v[208:211], v126
	ds_read_b128 v[212:215], v126 offset:8192
	s_waitcnt lgkmcnt(8)
	v_mfma_f32_32x32x16_bf16 v[48:63], v[98:101], v[152:155], v[48:63]
	v_cvt_pk_bf16_f32 v156, v72, v73
	v_add_f32_e32 v250, v68, v250
	v_add_f32_e32 v251, v69, v251
	v_mfma_f32_32x32x16_bf16 v[32:47], v[102:105], v[152:155], v[32:47]
	v_cvt_pk_bf16_f32 v157, v74, v75
	v_add_f32_e32 v250, v70, v250
	v_add_f32_e32 v251, v71, v251
	v_mfma_f32_32x32x16_bf16 v[16:31], v[106:109], v[152:155], v[16:31]
	v_cvt_pk_bf16_f32 v158, v76, v77
	v_add_f32_e32 v250, v72, v250
	v_add_f32_e32 v251, v73, v251
	v_mfma_f32_32x32x16_bf16 v[0:15], v[110:113], v[152:155], v[0:15]
	v_cvt_pk_bf16_f32 v159, v78, v79
	v_add_f32_e32 v250, v74, v250
	v_add_f32_e32 v251, v75, v251
	v_add_u32_e32 v97, s101, v179
	ds_read_b128 v[216:219], v97
	ds_read_b128 v[220:223], v97 offset:8192
	v_add_u32_e32 v126, s101, v180
	ds_read_b128 v[224:227], v126
	ds_read_b128 v[228:231], v126 offset:8192
	s_waitcnt lgkmcnt(8)
	v_mfma_f32_32x32x16_bf16 v[48:63], v[114:117], v[156:159], v[48:63]
	v_add_f32_e32 v250, v76, v250
	v_add_f32_e32 v251, v77, v251
	v_mfma_f32_32x32x16_bf16 v[32:47], v[118:121], v[156:159], v[32:47]
	v_add_f32_e32 v250, v78, v250
	v_add_f32_e32 v251, v79, v251
	v_mfma_f32_32x32x16_bf16 v[16:31], v[122:125], v[156:159], v[16:31]
	v_add_f32_e32 v250, v250, v251
	v_mfma_f32_32x32x16_bf16 v[0:15], v[196:199], v[156:159], v[0:15]
	v_add_f32_e32 v181, v181, v250
	s_setprio 0
